# v132 with ff1 U stores temporal (nt removed) for ff1->ff2 cache residency
# speedup vs baseline: 1.0233x; 1.0033x over previous
.LBB0_434:
	s_lshl_b32 s25, s28, 8
	s_lshl_b32 s28, s40, 20
	v_max_f32_e32 v127, v127, v127
	v_max_f32_e32 v126, v126, v126
	v_max_f32_e32 v129, v129, v129
	v_max_f32_e32 v128, v128, v128
	v_max_f32_e32 v123, v123, v123
	v_max_f32_e32 v122, v122, v122
	v_max_f32_e32 v125, v125, v125
	v_max_f32_e32 v124, v124, v124
	s_add_i32 s28, s28, s25
	v_max_f32_e32 v127, 0, v127
	v_max_f32_e32 v126, 0, v126
	v_max_f32_e32 v129, 0, v129
	v_max_f32_e32 v128, 0, v128
	v_max_f32_e32 v123, 0, v123
	v_max_f32_e32 v122, 0, v122
	v_max_f32_e32 v125, 0, v125
	v_max_f32_e32 v124, 0, v124
	v_max_f32_e32 v119, v119, v119
	v_max_f32_e32 v118, v118, v118
	v_add_u32_e32 v0, s28, v143
	v_pk_mul_f32 v[128:129], v[128:129], v[128:129]
	v_pk_mul_f32 v[126:127], v[126:127], v[126:127]
	v_pk_mul_f32 v[146:147], v[124:125], v[124:125]
	v_pk_mul_f32 v[124:125], v[122:123], v[122:123]
	v_max_f32_e32 v119, 0, v119
	v_max_f32_e32 v118, 0, v118
	v_max_f32_e32 v121, v121, v121
	v_max_f32_e32 v120, v120, v120
	v_max_f32_e32 v115, v115, v115
	v_max_f32_e32 v114, v114, v114
	v_max_f32_e32 v117, v117, v117
	v_max_f32_e32 v116, v116, v116
	v_cvt_pk_bf16_f32 v122, v126, v127
	v_cvt_pk_bf16_f32 v123, v128, v129
	v_cvt_pk_bf16_f32 v124, v124, v125
	v_cvt_pk_bf16_f32 v125, v146, v147
	v_lshl_add_u64 v[126:127], v[0:1], 1, s[52:53]
	v_max_f32_e32 v121, 0, v121
	v_max_f32_e32 v120, 0, v120
	v_max_f32_e32 v115, 0, v115
	v_max_f32_e32 v114, 0, v114
	v_max_f32_e32 v117, 0, v117
	v_max_f32_e32 v116, 0, v116
	v_pk_mul_f32 v[118:119], v[118:119], v[118:119]
	global_store_dwordx4 v[126:127], v[122:125], off
	v_pk_mul_f32 v[120:121], v[120:121], v[120:121]
	v_max_f32_e32 v111, v111, v111
	v_pk_mul_f32 v[122:123], v[116:117], v[116:117]
	v_pk_mul_f32 v[116:117], v[114:115], v[114:115]
	v_cvt_pk_bf16_f32 v114, v118, v119
	v_or_b32_e32 v118, 0x80, v0
	v_mov_b32_e32 v119, v1
	v_max_f32_e32 v110, v110, v110
	v_max_f32_e32 v113, v113, v113
	v_max_f32_e32 v112, v112, v112
	v_max_f32_e32 v107, v107, v107
	v_max_f32_e32 v106, v106, v106
	v_max_f32_e32 v109, v109, v109
	v_max_f32_e32 v108, v108, v108
	v_cvt_pk_bf16_f32 v115, v120, v121
	v_cvt_pk_bf16_f32 v116, v116, v117
	v_cvt_pk_bf16_f32 v117, v122, v123
	v_lshl_add_u64 v[118:119], v[118:119], 1, s[52:53]
	v_max_f32_e32 v111, 0, v111
	v_max_f32_e32 v110, 0, v110
	v_max_f32_e32 v113, 0, v113
	v_max_f32_e32 v112, 0, v112
	v_max_f32_e32 v107, 0, v107
	v_max_f32_e32 v106, 0, v106
	v_max_f32_e32 v109, 0, v109
	v_max_f32_e32 v108, 0, v108
	v_max_f32_e32 v103, v103, v103
	v_max_f32_e32 v102, v102, v102
	global_store_dwordx4 v[118:119], v[114:117], off
	v_pk_mul_f32 v[112:113], v[112:113], v[112:113]
	v_pk_mul_f32 v[110:111], v[110:111], v[110:111]
	v_add_u32_e32 v114, 0x10000, v0
	v_pk_mul_f32 v[116:117], v[108:109], v[108:109]
	v_pk_mul_f32 v[108:109], v[106:107], v[106:107]
	v_mov_b32_e32 v115, v1
	v_max_f32_e32 v103, 0, v103
	v_max_f32_e32 v102, 0, v102
	v_max_f32_e32 v105, v105, v105
	v_max_f32_e32 v104, v104, v104
	v_max_f32_e32 v99, v99, v99
	v_max_f32_e32 v98, v98, v98
	v_max_f32_e32 v101, v101, v101
	v_max_f32_e32 v100, v100, v100
	v_cvt_pk_bf16_f32 v106, v110, v111
	v_cvt_pk_bf16_f32 v107, v112, v113
	v_cvt_pk_bf16_f32 v108, v108, v109
	v_cvt_pk_bf16_f32 v109, v116, v117
	v_lshl_add_u64 v[110:111], v[114:115], 1, s[52:53]
	v_max_f32_e32 v105, 0, v105
	v_max_f32_e32 v104, 0, v104
	v_max_f32_e32 v99, 0, v99
	v_max_f32_e32 v98, 0, v98
	v_max_f32_e32 v101, 0, v101
	v_max_f32_e32 v100, 0, v100
	v_pk_mul_f32 v[102:103], v[102:103], v[102:103]
	global_store_dwordx4 v[110:111], v[106:109], off
	v_pk_mul_f32 v[104:105], v[104:105], v[104:105]
	v_max_f32_e32 v95, v95, v95
	v_pk_mul_f32 v[106:107], v[100:101], v[100:101]
	v_pk_mul_f32 v[100:101], v[98:99], v[98:99]
	v_cvt_pk_bf16_f32 v98, v102, v103
	v_add_u32_e32 v102, 0x10080, v0
	v_mov_b32_e32 v103, v1
	v_max_f32_e32 v94, v94, v94
	v_max_f32_e32 v97, v97, v97
	v_max_f32_e32 v96, v96, v96
	v_max_f32_e32 v91, v91, v91
	v_max_f32_e32 v90, v90, v90
	v_max_f32_e32 v93, v93, v93
	v_max_f32_e32 v92, v92, v92
	v_cvt_pk_bf16_f32 v99, v104, v105
	v_cvt_pk_bf16_f32 v100, v100, v101
	v_cvt_pk_bf16_f32 v101, v106, v107
	v_lshl_add_u64 v[102:103], v[102:103], 1, s[52:53]
	v_max_f32_e32 v95, 0, v95
	v_max_f32_e32 v94, 0, v94
	v_max_f32_e32 v97, 0, v97
	v_max_f32_e32 v96, 0, v96
	v_max_f32_e32 v91, 0, v91
	v_max_f32_e32 v90, 0, v90
	v_max_f32_e32 v93, 0, v93
	v_max_f32_e32 v92, 0, v92
	v_max_f32_e32 v87, v87, v87
	v_max_f32_e32 v86, v86, v86
	global_store_dwordx4 v[102:103], v[98:101], off
	v_pk_mul_f32 v[96:97], v[96:97], v[96:97]
	v_pk_mul_f32 v[94:95], v[94:95], v[94:95]
	v_add_u32_e32 v98, 0x20000, v0
	v_pk_mul_f32 v[100:101], v[92:93], v[92:93]
	v_pk_mul_f32 v[92:93], v[90:91], v[90:91]
	v_mov_b32_e32 v99, v1
	v_max_f32_e32 v87, 0, v87
	v_max_f32_e32 v86, 0, v86
	v_max_f32_e32 v89, v89, v89
	v_max_f32_e32 v88, v88, v88
	v_max_f32_e32 v83, v83, v83
	v_max_f32_e32 v82, v82, v82
	v_max_f32_e32 v85, v85, v85
	v_max_f32_e32 v84, v84, v84
	v_cvt_pk_bf16_f32 v90, v94, v95
	v_cvt_pk_bf16_f32 v91, v96, v97
	v_cvt_pk_bf16_f32 v92, v92, v93
	v_cvt_pk_bf16_f32 v93, v100, v101
	v_lshl_add_u64 v[94:95], v[98:99], 1, s[52:53]
	v_max_f32_e32 v89, 0, v89
	v_max_f32_e32 v88, 0, v88
	v_max_f32_e32 v83, 0, v83
	v_max_f32_e32 v82, 0, v82
	v_max_f32_e32 v85, 0, v85
	v_max_f32_e32 v84, 0, v84
	v_pk_mul_f32 v[86:87], v[86:87], v[86:87]
	global_store_dwordx4 v[94:95], v[90:93], off
	v_pk_mul_f32 v[88:89], v[88:89], v[88:89]
	v_max_f32_e32 v79, v79, v79
	v_pk_mul_f32 v[90:91], v[84:85], v[84:85]
	v_pk_mul_f32 v[84:85], v[82:83], v[82:83]
	v_cvt_pk_bf16_f32 v82, v86, v87
	v_add_u32_e32 v86, 0x20080, v0
	v_mov_b32_e32 v87, v1
	v_max_f32_e32 v78, v78, v78
	v_max_f32_e32 v81, v81, v81
	v_max_f32_e32 v80, v80, v80
	v_max_f32_e32 v75, v75, v75
	v_max_f32_e32 v74, v74, v74
	v_max_f32_e32 v77, v77, v77
	v_max_f32_e32 v76, v76, v76
	v_cvt_pk_bf16_f32 v83, v88, v89
	v_cvt_pk_bf16_f32 v84, v84, v85
	v_cvt_pk_bf16_f32 v85, v90, v91
	v_lshl_add_u64 v[86:87], v[86:87], 1, s[52:53]
	v_max_f32_e32 v79, 0, v79
	v_max_f32_e32 v78, 0, v78
	v_max_f32_e32 v81, 0, v81
	v_max_f32_e32 v80, 0, v80
	v_max_f32_e32 v75, 0, v75
	v_max_f32_e32 v74, 0, v74
	v_max_f32_e32 v77, 0, v77
	v_max_f32_e32 v76, 0, v76
	v_max_f32_e32 v71, v71, v71
	v_max_f32_e32 v70, v70, v70
	global_store_dwordx4 v[86:87], v[82:85], off
	v_pk_mul_f32 v[80:81], v[80:81], v[80:81]
	v_pk_mul_f32 v[78:79], v[78:79], v[78:79]
	v_add_u32_e32 v82, 0x30000, v0
	v_pk_mul_f32 v[84:85], v[76:77], v[76:77]
	v_pk_mul_f32 v[76:77], v[74:75], v[74:75]
	v_mov_b32_e32 v83, v1
	v_max_f32_e32 v71, 0, v71
	v_max_f32_e32 v70, 0, v70
	v_max_f32_e32 v73, v73, v73
	v_max_f32_e32 v72, v72, v72
	v_max_f32_e32 v67, v67, v67
	v_max_f32_e32 v66, v66, v66
	v_max_f32_e32 v69, v69, v69
	v_max_f32_e32 v68, v68, v68
	v_cvt_pk_bf16_f32 v74, v78, v79
	v_cvt_pk_bf16_f32 v75, v80, v81
	v_cvt_pk_bf16_f32 v76, v76, v77
	v_cvt_pk_bf16_f32 v77, v84, v85
	v_lshl_add_u64 v[78:79], v[82:83], 1, s[52:53]
	v_max_f32_e32 v73, 0, v73
	v_max_f32_e32 v72, 0, v72
	v_max_f32_e32 v67, 0, v67
	v_max_f32_e32 v66, 0, v66
	v_max_f32_e32 v69, 0, v69
	v_max_f32_e32 v68, 0, v68
	v_pk_mul_f32 v[70:71], v[70:71], v[70:71]
	global_store_dwordx4 v[78:79], v[74:77], off
	v_pk_mul_f32 v[72:73], v[72:73], v[72:73]
	v_max_f32_e32 v63, v63, v63
	v_pk_mul_f32 v[74:75], v[68:69], v[68:69]
	v_pk_mul_f32 v[68:69], v[66:67], v[66:67]
	v_cvt_pk_bf16_f32 v66, v70, v71
	v_add_u32_e32 v70, 0x30080, v0
	v_mov_b32_e32 v71, v1
	v_max_f32_e32 v62, v62, v62
	v_max_f32_e32 v65, v65, v65
	v_max_f32_e32 v64, v64, v64
	v_max_f32_e32 v59, v59, v59
	v_max_f32_e32 v58, v58, v58
	v_max_f32_e32 v61, v61, v61
	v_max_f32_e32 v60, v60, v60
	v_cvt_pk_bf16_f32 v67, v72, v73
	v_cvt_pk_bf16_f32 v68, v68, v69
	v_cvt_pk_bf16_f32 v69, v74, v75
	v_lshl_add_u64 v[70:71], v[70:71], 1, s[52:53]
	v_max_f32_e32 v63, 0, v63
	v_max_f32_e32 v62, 0, v62
	v_max_f32_e32 v65, 0, v65
	v_max_f32_e32 v64, 0, v64
	v_max_f32_e32 v59, 0, v59
	v_max_f32_e32 v58, 0, v58
	v_max_f32_e32 v61, 0, v61
	v_max_f32_e32 v60, 0, v60
	v_max_f32_e32 v55, v55, v55
	v_max_f32_e32 v54, v54, v54
	global_store_dwordx4 v[70:71], v[66:69], off
	v_pk_mul_f32 v[64:65], v[64:65], v[64:65]
	v_pk_mul_f32 v[62:63], v[62:63], v[62:63]
	v_add_u32_e32 v66, 0x80000, v0
	v_pk_mul_f32 v[68:69], v[60:61], v[60:61]
	v_pk_mul_f32 v[60:61], v[58:59], v[58:59]
	v_mov_b32_e32 v67, v1
	v_max_f32_e32 v55, 0, v55
	v_max_f32_e32 v54, 0, v54
	v_max_f32_e32 v57, v57, v57
	v_max_f32_e32 v56, v56, v56
	v_max_f32_e32 v51, v51, v51
	v_max_f32_e32 v50, v50, v50
	v_max_f32_e32 v53, v53, v53
	v_max_f32_e32 v52, v52, v52
	v_cvt_pk_bf16_f32 v58, v62, v63
	v_cvt_pk_bf16_f32 v59, v64, v65
	v_cvt_pk_bf16_f32 v60, v60, v61
	v_cvt_pk_bf16_f32 v61, v68, v69
	v_lshl_add_u64 v[62:63], v[66:67], 1, s[52:53]
	v_max_f32_e32 v57, 0, v57
	v_max_f32_e32 v56, 0, v56
	v_max_f32_e32 v51, 0, v51
	v_max_f32_e32 v50, 0, v50
	v_max_f32_e32 v53, 0, v53
	v_max_f32_e32 v52, 0, v52
	v_pk_mul_f32 v[54:55], v[54:55], v[54:55]
	global_store_dwordx4 v[62:63], v[58:61], off
	v_pk_mul_f32 v[56:57], v[56:57], v[56:57]
	v_max_f32_e32 v47, v47, v47
	v_pk_mul_f32 v[58:59], v[52:53], v[52:53]
	v_pk_mul_f32 v[52:53], v[50:51], v[50:51]
	v_cvt_pk_bf16_f32 v50, v54, v55
	v_add_u32_e32 v54, 0x80080, v0
	v_mov_b32_e32 v55, v1
	v_max_f32_e32 v46, v46, v46
	v_max_f32_e32 v49, v49, v49
	v_max_f32_e32 v48, v48, v48
	v_max_f32_e32 v43, v43, v43
	v_max_f32_e32 v42, v42, v42
	v_max_f32_e32 v45, v45, v45
	v_max_f32_e32 v44, v44, v44
	v_cvt_pk_bf16_f32 v51, v56, v57
	v_cvt_pk_bf16_f32 v52, v52, v53
	v_cvt_pk_bf16_f32 v53, v58, v59
	v_lshl_add_u64 v[54:55], v[54:55], 1, s[52:53]
	v_max_f32_e32 v47, 0, v47
	v_max_f32_e32 v46, 0, v46
	v_max_f32_e32 v49, 0, v49
	v_max_f32_e32 v48, 0, v48
	v_max_f32_e32 v43, 0, v43
	v_max_f32_e32 v42, 0, v42
	v_max_f32_e32 v45, 0, v45
	v_max_f32_e32 v44, 0, v44
	v_max_f32_e32 v39, v39, v39
	v_max_f32_e32 v38, v38, v38
	global_store_dwordx4 v[54:55], v[50:53], off
	v_pk_mul_f32 v[48:49], v[48:49], v[48:49]
	v_pk_mul_f32 v[46:47], v[46:47], v[46:47]
	v_add_u32_e32 v50, 0x90000, v0
	v_pk_mul_f32 v[52:53], v[44:45], v[44:45]
	v_pk_mul_f32 v[44:45], v[42:43], v[42:43]
	v_mov_b32_e32 v51, v1
	v_max_f32_e32 v39, 0, v39
	v_max_f32_e32 v38, 0, v38
	v_max_f32_e32 v41, v41, v41
	v_max_f32_e32 v40, v40, v40
	v_max_f32_e32 v35, v35, v35
	v_max_f32_e32 v34, v34, v34
	v_max_f32_e32 v37, v37, v37
	v_max_f32_e32 v36, v36, v36
	v_cvt_pk_bf16_f32 v42, v46, v47
	v_cvt_pk_bf16_f32 v43, v48, v49
	v_cvt_pk_bf16_f32 v44, v44, v45
	v_cvt_pk_bf16_f32 v45, v52, v53
	v_lshl_add_u64 v[46:47], v[50:51], 1, s[52:53]
	v_max_f32_e32 v41, 0, v41
	v_max_f32_e32 v40, 0, v40
	v_max_f32_e32 v35, 0, v35
	v_max_f32_e32 v34, 0, v34
	v_max_f32_e32 v37, 0, v37
	v_max_f32_e32 v36, 0, v36
	v_pk_mul_f32 v[38:39], v[38:39], v[38:39]
	global_store_dwordx4 v[46:47], v[42:45], off
	v_pk_mul_f32 v[40:41], v[40:41], v[40:41]
	v_max_f32_e32 v31, v31, v31
	v_pk_mul_f32 v[42:43], v[36:37], v[36:37]
	v_pk_mul_f32 v[36:37], v[34:35], v[34:35]
	v_cvt_pk_bf16_f32 v34, v38, v39
	v_add_u32_e32 v38, 0x90080, v0
	v_mov_b32_e32 v39, v1
	v_max_f32_e32 v30, v30, v30
	v_max_f32_e32 v33, v33, v33
	v_max_f32_e32 v32, v32, v32
	v_max_f32_e32 v27, v27, v27
	v_max_f32_e32 v26, v26, v26
	v_max_f32_e32 v29, v29, v29
	v_max_f32_e32 v28, v28, v28
	v_cvt_pk_bf16_f32 v35, v40, v41
	v_cvt_pk_bf16_f32 v36, v36, v37
	v_cvt_pk_bf16_f32 v37, v42, v43
	v_lshl_add_u64 v[38:39], v[38:39], 1, s[52:53]
	v_max_f32_e32 v31, 0, v31
	v_max_f32_e32 v30, 0, v30
	v_max_f32_e32 v33, 0, v33
	v_max_f32_e32 v32, 0, v32
	v_max_f32_e32 v27, 0, v27
	v_max_f32_e32 v26, 0, v26
	v_max_f32_e32 v29, 0, v29
	v_max_f32_e32 v28, 0, v28
	v_max_f32_e32 v23, v23, v23
	v_max_f32_e32 v22, v22, v22
	global_store_dwordx4 v[38:39], v[34:37], off
	v_pk_mul_f32 v[32:33], v[32:33], v[32:33]
	v_pk_mul_f32 v[30:31], v[30:31], v[30:31]
	v_add_u32_e32 v34, 0xa0000, v0
	v_pk_mul_f32 v[36:37], v[28:29], v[28:29]
	v_pk_mul_f32 v[28:29], v[26:27], v[26:27]
	v_mov_b32_e32 v35, v1
	v_max_f32_e32 v23, 0, v23
	v_max_f32_e32 v22, 0, v22
	v_max_f32_e32 v25, v25, v25
	v_max_f32_e32 v24, v24, v24
	v_max_f32_e32 v19, v19, v19
	v_max_f32_e32 v18, v18, v18
	v_max_f32_e32 v21, v21, v21
	v_max_f32_e32 v20, v20, v20
	v_cvt_pk_bf16_f32 v26, v30, v31
	v_cvt_pk_bf16_f32 v27, v32, v33
	v_cvt_pk_bf16_f32 v28, v28, v29
	v_cvt_pk_bf16_f32 v29, v36, v37
	v_lshl_add_u64 v[30:31], v[34:35], 1, s[52:53]
	v_max_f32_e32 v25, 0, v25
	v_max_f32_e32 v24, 0, v24
	v_max_f32_e32 v19, 0, v19
	v_max_f32_e32 v18, 0, v18
	v_max_f32_e32 v21, 0, v21
	v_max_f32_e32 v20, 0, v20
	v_pk_mul_f32 v[22:23], v[22:23], v[22:23]
	global_store_dwordx4 v[30:31], v[26:29], off
	v_pk_mul_f32 v[24:25], v[24:25], v[24:25]
	v_max_f32_e32 v15, v15, v15
	v_pk_mul_f32 v[26:27], v[20:21], v[20:21]
	v_pk_mul_f32 v[20:21], v[18:19], v[18:19]
	v_cvt_pk_bf16_f32 v18, v22, v23
	v_add_u32_e32 v22, 0xa0080, v0
	v_mov_b32_e32 v23, v1
	v_max_f32_e32 v14, v14, v14
	v_max_f32_e32 v17, v17, v17
	v_max_f32_e32 v16, v16, v16
	v_max_f32_e32 v11, v11, v11
	v_max_f32_e32 v10, v10, v10
	v_max_f32_e32 v13, v13, v13
	v_max_f32_e32 v12, v12, v12
	v_cvt_pk_bf16_f32 v19, v24, v25
	v_cvt_pk_bf16_f32 v20, v20, v21
	v_cvt_pk_bf16_f32 v21, v26, v27
	v_lshl_add_u64 v[22:23], v[22:23], 1, s[52:53]
	v_max_f32_e32 v15, 0, v15
	v_max_f32_e32 v14, 0, v14
	v_max_f32_e32 v17, 0, v17
	v_max_f32_e32 v16, 0, v16
	v_max_f32_e32 v11, 0, v11
	v_max_f32_e32 v10, 0, v10
	v_max_f32_e32 v13, 0, v13
	v_max_f32_e32 v12, 0, v12
	global_store_dwordx4 v[22:23], v[18:21], off
	v_pk_mul_f32 v[16:17], v[16:17], v[16:17]
	v_pk_mul_f32 v[14:15], v[14:15], v[14:15]
	v_add_u32_e32 v18, 0xb0000, v0
	v_pk_mul_f32 v[20:21], v[12:13], v[12:13]
	v_pk_mul_f32 v[12:13], v[10:11], v[10:11]
	v_mov_b32_e32 v19, v1
	v_max_f32_e32 v7, v7, v7
	v_max_f32_e32 v6, v6, v6
	v_max_f32_e32 v9, v9, v9
	v_max_f32_e32 v8, v8, v8
	v_max_f32_e32 v3, v3, v3
	v_max_f32_e32 v2, v2, v2
	v_max_f32_e32 v5, v5, v5
	v_max_f32_e32 v4, v4, v4
	v_cvt_pk_bf16_f32 v10, v14, v15
	v_cvt_pk_bf16_f32 v11, v16, v17
	v_cvt_pk_bf16_f32 v12, v12, v13
	v_cvt_pk_bf16_f32 v13, v20, v21
	v_lshl_add_u64 v[14:15], v[18:19], 1, s[52:53]
	v_max_f32_e32 v7, 0, v7
	v_max_f32_e32 v6, 0, v6
	v_max_f32_e32 v9, 0, v9
	v_max_f32_e32 v8, 0, v8
	v_max_f32_e32 v3, 0, v3
	v_max_f32_e32 v2, 0, v2
	v_max_f32_e32 v5, 0, v5
	v_max_f32_e32 v4, 0, v4
	global_store_dwordx4 v[14:15], v[10:13], off
	v_pk_mul_f32 v[8:9], v[8:9], v[8:9]
	v_pk_mul_f32 v[6:7], v[6:7], v[6:7]
	v_pk_mul_f32 v[10:11], v[4:5], v[4:5]
	v_pk_mul_f32 v[4:5], v[2:3], v[2:3]
	v_add_u32_e32 v0, 0xb0080, v0
	v_cvt_pk_bf16_f32 v2, v6, v7
	v_cvt_pk_bf16_f32 v3, v8, v9
	v_cvt_pk_bf16_f32 v4, v4, v5
	v_cvt_pk_bf16_f32 v5, v10, v11
	v_lshl_add_u64 v[6:7], v[0:1], 1, s[52:53]
	s_andn2_b64 vcc, exec, s[38:39]
	s_mov_b64 s[38:39], -1
	v_readlane_b32 s47, v254, 61
	global_store_dwordx4 v[6:7], v[2:5], off
	s_cbranch_vccnz .LBB0_427
	s_andn2_b64 vcc, exec, s[2:3]
	s_cbranch_vccnz .LBB0_426
	s_barrier
	s_branch .LBB0_426
